# SwiGLU epilogue arithmetic re-emitted in packed 4-wide batches without hazard nops (same operations and order per element)
# speedup vs baseline: 1.0282x; 1.0096x over previous
; __device__ __forceinline__ unsigned cvt_pk_bf16(float lo, float hi) { const f32x2 v = {lo, hi}; return __builtin_bit_cast(unsigned, __builtin_convertvector(v, bf16v2_t)); }
; __device__ __forceinline__ float fexp(float v) { return __builtin_amdgcn_exp2f(v * 1.4426950408889634f); }
; __device__ __forceinline__ float silu_f(float v) { return v * __builtin_amdgcn_rcpf(1.0f + fexp(-v)); }
;     __device__ __forceinline__ void operator()(const f32x4 (&acc)[2][2][4][2], const pg8::Unit& u, int wr, int wc, int fr, int fq) const {
;         const int row0 = u.pm * 256 + wr * 64 + fr, hc0 = u.pn * 128 + wc * 32 + 8 * fq;
; #pragma unroll
;         for (int ai = 0; ai < 2; ++ai)
; #pragma unroll
;             for (int m = 0; m < 4; ++m) { u32x4 w;
; #pragma unroll
;                 for (int n = 0; n < 2; ++n) { const f32x4 a = acc[ai][0][m][n], b = acc[ai][1][m][n];
;                     w[2 * n] = cvt_pk_bf16(silu_f(a[0]) * b[0], silu_f(a[1]) * b[1]); w[2 * n + 1] = cvt_pk_bf16(silu_f(a[2]) * b[2], silu_f(a[3]) * b[3]); }
;                 const int row = row0 + ai * 128 + m * 16;
;                 *(u32x4*)(hid + ((size_t)((row >> 8) * (DFF / 64) + (hc0 >> 6)) * 2 + ((row >> 7) & 1)) * 8192 + (row & 127) * 64 + (hc0 & 63)) = w; }
.LBB0_614:
	v_mov_b32_e32 v214, 0xbfb8aa3b
	v_mov_b32_e32 v215, 0xbfb8aa3b
	v_pk_mul_f32 v[206:207], v[126:127], v[214:215] op_sel_hi:[1,0]
	v_pk_mul_f32 v[208:209], v[128:129], v[214:215] op_sel_hi:[1,0]
	v_pk_mul_f32 v[210:211], v[118:119], v[214:215] op_sel_hi:[1,0]
	v_pk_mul_f32 v[212:213], v[120:121], v[214:215] op_sel_hi:[1,0]
	v_exp_f32_e32 v206, v206
	v_exp_f32_e32 v207, v207
	v_exp_f32_e32 v208, v208
	v_exp_f32_e32 v209, v209
	v_exp_f32_e32 v210, v210
	v_exp_f32_e32 v211, v211
	v_exp_f32_e32 v212, v212
	v_exp_f32_e32 v213, v213
	v_pk_add_f32 v[206:207], v[206:207], 1.0 op_sel_hi:[1,0]
	v_pk_add_f32 v[208:209], v[208:209], 1.0 op_sel_hi:[1,0]
	v_pk_add_f32 v[210:211], v[210:211], 1.0 op_sel_hi:[1,0]
	v_pk_add_f32 v[212:213], v[212:213], 1.0 op_sel_hi:[1,0]
	v_rcp_f32_e32 v206, v206
	v_rcp_f32_e32 v207, v207
	v_rcp_f32_e32 v208, v208
	v_rcp_f32_e32 v209, v209
	v_rcp_f32_e32 v210, v210
	v_rcp_f32_e32 v211, v211
	v_rcp_f32_e32 v212, v212
	v_rcp_f32_e32 v213, v213
	v_pk_mul_f32 v[206:207], v[126:127], v[206:207]
	v_pk_mul_f32 v[208:209], v[128:129], v[208:209]
	v_pk_mul_f32 v[210:211], v[118:119], v[210:211]
	v_pk_mul_f32 v[212:213], v[120:121], v[212:213]
	v_pk_mul_f32 v[206:207], v[206:207], v[122:123]
	v_pk_mul_f32 v[208:209], v[208:209], v[124:125]
	v_pk_mul_f32 v[210:211], v[210:211], v[114:115]
	v_pk_mul_f32 v[212:213], v[212:213], v[116:117]
	v_cvt_pk_bf16_f32 v122, v206, v207
	v_cvt_pk_bf16_f32 v123, v208, v209
	v_cvt_pk_bf16_f32 v124, v210, v211
	v_cvt_pk_bf16_f32 v125, v212, v213
	s_lshl_b32 s13, s18, 8
	s_add_i32 s13, s13, s38
	s_lshl_b32 s11, s19, 7
	s_or_b32 s11, s11, s39
	s_ashr_i32 s18, s13, 8
	s_ashr_i32 s11, s11, 6
	s_mul_i32 s18, s18, 44
	s_add_i32 s18, s18, s11
	s_ashr_i32 s19, s18, 31
	s_lshl_b64 s[18:19], s[18:19], 15
	v_readlane_b32 s20, v249, 53
	v_readlane_b32 s21, v249, 54
	s_add_u32 s18, s20, s18
	v_or_b32_e32 v143, s13, v140
	s_addc_u32 s19, s21, s19
	s_lshl_b32 s13, s13, 7
	s_and_b32 s13, s13, 0x4000
	s_add_u32 s18, s18, s13
	s_addc_u32 s19, s19, 0
	v_mov_b32_e32 v139, v1
	v_lshlrev_b32_e32 v0, 7, v143
	v_and_b32_e32 v0, 0x2780, v0
	s_andn2_b64 vcc, exec, s[0:1]
	v_lshl_add_u64 v[114:115], s[18:19], 0, v[0:1]
	v_lshl_add_u64 v[114:115], v[114:115], 0, v[138:139]
	global_store_dwordx4 v[114:115], v[122:125], off
	v_pk_mul_f32 v[206:207], v[110:111], v[214:215] op_sel_hi:[1,0]
	v_pk_mul_f32 v[208:209], v[112:113], v[214:215] op_sel_hi:[1,0]
	v_pk_mul_f32 v[210:211], v[102:103], v[214:215] op_sel_hi:[1,0]
	v_pk_mul_f32 v[212:213], v[104:105], v[214:215] op_sel_hi:[1,0]
	v_exp_f32_e32 v206, v206
	v_exp_f32_e32 v207, v207
	v_exp_f32_e32 v208, v208
	v_exp_f32_e32 v209, v209
	v_exp_f32_e32 v210, v210
	v_exp_f32_e32 v211, v211
	v_exp_f32_e32 v212, v212
	v_exp_f32_e32 v213, v213
	v_pk_add_f32 v[206:207], v[206:207], 1.0 op_sel_hi:[1,0]
	v_pk_add_f32 v[208:209], v[208:209], 1.0 op_sel_hi:[1,0]
	v_pk_add_f32 v[210:211], v[210:211], 1.0 op_sel_hi:[1,0]
	v_pk_add_f32 v[212:213], v[212:213], 1.0 op_sel_hi:[1,0]
	v_rcp_f32_e32 v206, v206
	v_rcp_f32_e32 v207, v207
	v_rcp_f32_e32 v208, v208
	v_rcp_f32_e32 v209, v209
	v_rcp_f32_e32 v210, v210
	v_rcp_f32_e32 v211, v211
	v_rcp_f32_e32 v212, v212
	v_rcp_f32_e32 v213, v213
	v_pk_mul_f32 v[206:207], v[110:111], v[206:207]
	v_pk_mul_f32 v[208:209], v[112:113], v[208:209]
	v_pk_mul_f32 v[210:211], v[102:103], v[210:211]
	v_pk_mul_f32 v[212:213], v[104:105], v[212:213]
	v_pk_mul_f32 v[206:207], v[206:207], v[106:107]
	v_pk_mul_f32 v[208:209], v[208:209], v[108:109]
	v_pk_mul_f32 v[210:211], v[210:211], v[98:99]
	v_pk_mul_f32 v[212:213], v[212:213], v[100:101]
	v_cvt_pk_bf16_f32 v106, v206, v207
	v_cvt_pk_bf16_f32 v107, v208, v209
	v_cvt_pk_bf16_f32 v108, v210, v211
	v_cvt_pk_bf16_f32 v109, v212, v213
	global_store_dwordx4 v[114:115], v[106:109], off offset:2048
	v_pk_mul_f32 v[206:207], v[94:95], v[214:215] op_sel_hi:[1,0]
	v_pk_mul_f32 v[208:209], v[96:97], v[214:215] op_sel_hi:[1,0]
	v_pk_mul_f32 v[210:211], v[86:87], v[214:215] op_sel_hi:[1,0]
	v_pk_mul_f32 v[212:213], v[88:89], v[214:215] op_sel_hi:[1,0]
	v_exp_f32_e32 v206, v206
	v_exp_f32_e32 v207, v207
	v_exp_f32_e32 v208, v208
	v_exp_f32_e32 v209, v209
	v_exp_f32_e32 v210, v210
	v_exp_f32_e32 v211, v211
	v_exp_f32_e32 v212, v212
	v_exp_f32_e32 v213, v213
	v_pk_add_f32 v[206:207], v[206:207], 1.0 op_sel_hi:[1,0]
	v_pk_add_f32 v[208:209], v[208:209], 1.0 op_sel_hi:[1,0]
	v_pk_add_f32 v[210:211], v[210:211], 1.0 op_sel_hi:[1,0]
	v_pk_add_f32 v[212:213], v[212:213], 1.0 op_sel_hi:[1,0]
	v_rcp_f32_e32 v206, v206
	v_rcp_f32_e32 v207, v207
	v_rcp_f32_e32 v208, v208
	v_rcp_f32_e32 v209, v209
	v_rcp_f32_e32 v210, v210
	v_rcp_f32_e32 v211, v211
	v_rcp_f32_e32 v212, v212
	v_rcp_f32_e32 v213, v213
	v_pk_mul_f32 v[206:207], v[94:95], v[206:207]
	v_pk_mul_f32 v[208:209], v[96:97], v[208:209]
	v_pk_mul_f32 v[210:211], v[86:87], v[210:211]
	v_pk_mul_f32 v[212:213], v[88:89], v[212:213]
	v_pk_mul_f32 v[206:207], v[206:207], v[90:91]
	v_pk_mul_f32 v[208:209], v[208:209], v[92:93]
	v_pk_mul_f32 v[210:211], v[210:211], v[82:83]
	v_pk_mul_f32 v[212:213], v[212:213], v[84:85]
	v_cvt_pk_bf16_f32 v90, v206, v207
	v_cvt_pk_bf16_f32 v91, v208, v209
	v_cvt_pk_bf16_f32 v92, v210, v211
	v_cvt_pk_bf16_f32 v93, v212, v213
	v_or_b32_e32 v82, 0x1000, v0
	v_mov_b32_e32 v83, v1
	v_lshl_add_u64 v[84:85], s[18:19], 0, v[82:83]
	v_lshl_add_u64 v[84:85], v[84:85], 0, v[138:139]
	global_store_dwordx4 v[84:85], v[90:93], off
	v_pk_mul_f32 v[206:207], v[78:79], v[214:215] op_sel_hi:[1,0]
	v_pk_mul_f32 v[208:209], v[80:81], v[214:215] op_sel_hi:[1,0]
	v_pk_mul_f32 v[210:211], v[70:71], v[214:215] op_sel_hi:[1,0]
	v_pk_mul_f32 v[212:213], v[72:73], v[214:215] op_sel_hi:[1,0]
; __device__ __forceinline__ unsigned cvt_pk_bf16(float lo, float hi) { const f32x2 v = {lo, hi}; return __builtin_bit_cast(unsigned, __builtin_convertvector(v, bf16v2_t)); }
; __device__ __forceinline__ float fexp(float v) { return __builtin_amdgcn_exp2f(v * 1.4426950408889634f); }
; __device__ __forceinline__ float silu_f(float v) { return v * __builtin_amdgcn_rcpf(1.0f + fexp(-v)); }
;     __device__ __forceinline__ void operator()(const f32x4 (&acc)[2][2][4][2], const pg8::Unit& u, int wr, int wc, int fr, int fq) const {
;         const int row0 = u.pm * 256 + wr * 64 + fr, hc0 = u.pn * 128 + wc * 32 + 8 * fq;
; #pragma unroll
;         for (int ai = 0; ai < 2; ++ai)
; #pragma unroll
;             for (int m = 0; m < 4; ++m) { u32x4 w;
; #pragma unroll
;                 for (int n = 0; n < 2; ++n) { const f32x4 a = acc[ai][0][m][n], b = acc[ai][1][m][n];
;                     w[2 * n] = cvt_pk_bf16(silu_f(a[0]) * b[0], silu_f(a[1]) * b[1]); w[2 * n + 1] = cvt_pk_bf16(silu_f(a[2]) * b[2], silu_f(a[3]) * b[3]); }
;                 const int row = row0 + ai * 128 + m * 16;
;                 *(u32x4*)(hid + ((size_t)((row >> 8) * (DFF / 64) + (hc0 >> 6)) * 2 + ((row >> 7) & 1)) * 8192 + (row & 127) * 64 + (hc0 & 63)) = w; }
	v_exp_f32_e32 v206, v206
	v_exp_f32_e32 v207, v207
	v_exp_f32_e32 v208, v208
	v_exp_f32_e32 v209, v209
	v_exp_f32_e32 v210, v210
	v_exp_f32_e32 v211, v211
	v_exp_f32_e32 v212, v212
	v_exp_f32_e32 v213, v213
	v_pk_add_f32 v[206:207], v[206:207], 1.0 op_sel_hi:[1,0]
	v_pk_add_f32 v[208:209], v[208:209], 1.0 op_sel_hi:[1,0]
	v_pk_add_f32 v[210:211], v[210:211], 1.0 op_sel_hi:[1,0]
	v_pk_add_f32 v[212:213], v[212:213], 1.0 op_sel_hi:[1,0]
	v_rcp_f32_e32 v206, v206
	v_rcp_f32_e32 v207, v207
	v_rcp_f32_e32 v208, v208
	v_rcp_f32_e32 v209, v209
	v_rcp_f32_e32 v210, v210
	v_rcp_f32_e32 v211, v211
	v_rcp_f32_e32 v212, v212
	v_rcp_f32_e32 v213, v213
	v_pk_mul_f32 v[206:207], v[78:79], v[206:207]
	v_pk_mul_f32 v[208:209], v[80:81], v[208:209]
	v_pk_mul_f32 v[210:211], v[70:71], v[210:211]
	v_pk_mul_f32 v[212:213], v[72:73], v[212:213]
	v_pk_mul_f32 v[206:207], v[206:207], v[74:75]
	v_pk_mul_f32 v[208:209], v[208:209], v[76:77]
	v_pk_mul_f32 v[210:211], v[210:211], v[66:67]
	v_pk_mul_f32 v[212:213], v[212:213], v[68:69]
	v_cvt_pk_bf16_f32 v74, v206, v207
	v_cvt_pk_bf16_f32 v75, v208, v209
	v_cvt_pk_bf16_f32 v76, v210, v211
	v_cvt_pk_bf16_f32 v77, v212, v213
	v_add_u32_e32 v72, 0x80, v143
	v_or_b32_e32 v66, 0x1800, v0
	v_mov_b32_e32 v67, v1
	v_lshl_add_u64 v[68:69], s[18:19], 0, v[66:67]
	v_lshl_add_u64 v[68:69], v[68:69], 0, v[138:139]
	global_store_dwordx4 v[68:69], v[74:77], off
	v_pk_mul_f32 v[206:207], v[62:63], v[214:215] op_sel_hi:[1,0]
	v_pk_mul_f32 v[208:209], v[64:65], v[214:215] op_sel_hi:[1,0]
	v_pk_mul_f32 v[210:211], v[54:55], v[214:215] op_sel_hi:[1,0]
	v_pk_mul_f32 v[212:213], v[56:57], v[214:215] op_sel_hi:[1,0]
	v_exp_f32_e32 v206, v206
	v_exp_f32_e32 v207, v207
	v_exp_f32_e32 v208, v208
	v_exp_f32_e32 v209, v209
	v_exp_f32_e32 v210, v210
	v_exp_f32_e32 v211, v211
	v_exp_f32_e32 v212, v212
	v_exp_f32_e32 v213, v213
	v_pk_add_f32 v[206:207], v[206:207], 1.0 op_sel_hi:[1,0]
	v_pk_add_f32 v[208:209], v[208:209], 1.0 op_sel_hi:[1,0]
	v_pk_add_f32 v[210:211], v[210:211], 1.0 op_sel_hi:[1,0]
	v_pk_add_f32 v[212:213], v[212:213], 1.0 op_sel_hi:[1,0]
	v_rcp_f32_e32 v206, v206
	v_rcp_f32_e32 v207, v207
	v_rcp_f32_e32 v208, v208
	v_rcp_f32_e32 v209, v209
	v_rcp_f32_e32 v210, v210
	v_rcp_f32_e32 v211, v211
	v_rcp_f32_e32 v212, v212
	v_rcp_f32_e32 v213, v213
	v_pk_mul_f32 v[206:207], v[62:63], v[206:207]
	v_pk_mul_f32 v[208:209], v[64:65], v[208:209]
	v_pk_mul_f32 v[210:211], v[54:55], v[210:211]
	v_pk_mul_f32 v[212:213], v[56:57], v[212:213]
	v_pk_mul_f32 v[206:207], v[206:207], v[58:59]
	v_pk_mul_f32 v[208:209], v[208:209], v[60:61]
	v_pk_mul_f32 v[210:211], v[210:211], v[50:51]
	v_pk_mul_f32 v[212:213], v[212:213], v[52:53]
	v_cvt_pk_bf16_f32 v58, v206, v207
	v_cvt_pk_bf16_f32 v59, v208, v209
	v_cvt_pk_bf16_f32 v60, v210, v211
	v_cvt_pk_bf16_f32 v61, v212, v213
	v_lshrrev_b32_e32 v68, 8, v72
	v_mad_i32_i24 v68, v68, 44, s11
	v_ashrrev_i32_e32 v69, 31, v68
	v_lshlrev_b64 v[68:69], 15, v[68:69]
	s_mov_b64 s[18:19], -1
	v_lshlrev_b32_e32 v52, 7, v72
	v_lshl_add_u64 v[50:51], s[20:21], 0, v[68:69]
	v_and_b32_e32 v52, 0x4000, v52
	v_mov_b32_e32 v53, v1
	v_lshl_add_u64 v[50:51], v[50:51], 0, v[52:53]
	v_lshl_add_u64 v[52:53], v[50:51], 0, v[0:1]
	v_lshl_add_u64 v[52:53], v[52:53], 0, v[138:139]
	global_store_dwordx4 v[52:53], v[58:61], off
	v_pk_mul_f32 v[206:207], v[46:47], v[214:215] op_sel_hi:[1,0]
	v_pk_mul_f32 v[208:209], v[48:49], v[214:215] op_sel_hi:[1,0]
	v_pk_mul_f32 v[210:211], v[38:39], v[214:215] op_sel_hi:[1,0]
	v_pk_mul_f32 v[212:213], v[40:41], v[214:215] op_sel_hi:[1,0]
	v_exp_f32_e32 v206, v206
	v_exp_f32_e32 v207, v207
	v_exp_f32_e32 v208, v208
	v_exp_f32_e32 v209, v209
	v_exp_f32_e32 v210, v210
	v_exp_f32_e32 v211, v211
	v_exp_f32_e32 v212, v212
	v_exp_f32_e32 v213, v213
	v_pk_add_f32 v[206:207], v[206:207], 1.0 op_sel_hi:[1,0]
	v_pk_add_f32 v[208:209], v[208:209], 1.0 op_sel_hi:[1,0]
	v_pk_add_f32 v[210:211], v[210:211], 1.0 op_sel_hi:[1,0]
	v_pk_add_f32 v[212:213], v[212:213], 1.0 op_sel_hi:[1,0]
; __device__ __forceinline__ unsigned cvt_pk_bf16(float lo, float hi) { const f32x2 v = {lo, hi}; return __builtin_bit_cast(unsigned, __builtin_convertvector(v, bf16v2_t)); }
; __device__ __forceinline__ float silu_f(float v) { return v * __builtin_amdgcn_rcpf(1.0f + fexp(-v)); }
; #define PG8_BAR __builtin_amdgcn_s_barrier()
; template <class Epi, bool ALIGN_EPI = PG8_ALIGN, bool SP2 = PG8_SP2>
; __device__ __forceinline__ void gemm_phase(LAS unsigned char* lds, const Gemm g, const StaticOrder& S, const Epi& E) {
;     ...
;         if (!has_next) break;
; #pragma unroll
;         for (int a = 0; a < 2; ++a)
; #pragma unroll
;             for (int b = 0; b < 2; ++b)
; #pragma unroll
;                 for (int m = 0; m < 4; ++m)
; #pragma unroll
;                     for (int n = 0; n < 2; ++n) acc[a][b][m][n] = (f32x4){0.f, 0.f, 0.f, 0.f};
;         cur = nxt; cA = nA; cB = nB; ++ui;
;         if constexpr (ALIGN_EPI) { if (wr == 1) PG8_BAR; }
;     __device__ __forceinline__ void operator()(const f32x4 (&acc)[2][2][4][2], const pg8::Unit& u, int wr, int wc, int fr, int fq) const {
;     ...
;             for (int m = 0; m < 4; ++m) { u32x4 w;
; #pragma unroll
;                 for (int n = 0; n < 2; ++n) { const f32x4 a = acc[ai][0][m][n], b = acc[ai][1][m][n];
;                     w[2 * n] = cvt_pk_bf16(silu_f(a[0]) * b[0], silu_f(a[1]) * b[1]); w[2 * n + 1] = cvt_pk_bf16(silu_f(a[2]) * b[2], silu_f(a[3]) * b[3]); }
;                 const int row = row0 + ai * 128 + m * 16;
;                 *(u32x4*)(hid + ((size_t)((row >> 8) * (DFF / 64) + (hc0 >> 6)) * 2 + ((row >> 7) & 1)) * 8192 + (row & 127) * 64 + (hc0 & 63)) = w; }
	v_rcp_f32_e32 v206, v206
	v_rcp_f32_e32 v207, v207
	v_rcp_f32_e32 v208, v208
	v_rcp_f32_e32 v209, v209
	v_rcp_f32_e32 v210, v210
	v_rcp_f32_e32 v211, v211
	v_rcp_f32_e32 v212, v212
	v_rcp_f32_e32 v213, v213
	v_pk_mul_f32 v[206:207], v[46:47], v[206:207]
	v_pk_mul_f32 v[208:209], v[48:49], v[208:209]
	v_pk_mul_f32 v[210:211], v[38:39], v[210:211]
	v_pk_mul_f32 v[212:213], v[40:41], v[212:213]
	v_pk_mul_f32 v[206:207], v[206:207], v[42:43]
	v_pk_mul_f32 v[208:209], v[208:209], v[44:45]
	v_pk_mul_f32 v[210:211], v[210:211], v[34:35]
	v_pk_mul_f32 v[212:213], v[212:213], v[36:37]
	v_cvt_pk_bf16_f32 v42, v206, v207
	v_cvt_pk_bf16_f32 v43, v208, v209
	v_cvt_pk_bf16_f32 v44, v210, v211
	v_cvt_pk_bf16_f32 v45, v212, v213
	global_store_dwordx4 v[52:53], v[42:45], off offset:2048
	v_pk_mul_f32 v[206:207], v[30:31], v[214:215] op_sel_hi:[1,0]
	v_pk_mul_f32 v[208:209], v[32:33], v[214:215] op_sel_hi:[1,0]
	v_pk_mul_f32 v[210:211], v[22:23], v[214:215] op_sel_hi:[1,0]
	v_pk_mul_f32 v[212:213], v[24:25], v[214:215] op_sel_hi:[1,0]
	v_exp_f32_e32 v206, v206
	v_exp_f32_e32 v207, v207
	v_exp_f32_e32 v208, v208
	v_exp_f32_e32 v209, v209
	v_exp_f32_e32 v210, v210
	v_exp_f32_e32 v211, v211
	v_exp_f32_e32 v212, v212
	v_exp_f32_e32 v213, v213
	v_pk_add_f32 v[206:207], v[206:207], 1.0 op_sel_hi:[1,0]
	v_pk_add_f32 v[208:209], v[208:209], 1.0 op_sel_hi:[1,0]
	v_pk_add_f32 v[210:211], v[210:211], 1.0 op_sel_hi:[1,0]
	v_pk_add_f32 v[212:213], v[212:213], 1.0 op_sel_hi:[1,0]
	v_rcp_f32_e32 v206, v206
	v_rcp_f32_e32 v207, v207
	v_rcp_f32_e32 v208, v208
	v_rcp_f32_e32 v209, v209
	v_rcp_f32_e32 v210, v210
	v_rcp_f32_e32 v211, v211
	v_rcp_f32_e32 v212, v212
	v_rcp_f32_e32 v213, v213
	v_pk_mul_f32 v[206:207], v[30:31], v[206:207]
	v_pk_mul_f32 v[208:209], v[32:33], v[208:209]
	v_pk_mul_f32 v[210:211], v[22:23], v[210:211]
	v_pk_mul_f32 v[212:213], v[24:25], v[212:213]
	v_pk_mul_f32 v[206:207], v[206:207], v[26:27]
	v_pk_mul_f32 v[208:209], v[208:209], v[28:29]
	v_pk_mul_f32 v[210:211], v[210:211], v[18:19]
	v_pk_mul_f32 v[212:213], v[212:213], v[20:21]
	v_cvt_pk_bf16_f32 v26, v206, v207
	v_cvt_pk_bf16_f32 v27, v208, v209
	v_cvt_pk_bf16_f32 v28, v210, v211
	v_cvt_pk_bf16_f32 v29, v212, v213
	v_lshl_add_u64 v[18:19], v[50:51], 0, v[82:83]
	v_lshl_add_u64 v[18:19], v[18:19], 0, v[138:139]
	global_store_dwordx4 v[18:19], v[26:29], off
	v_pk_mul_f32 v[206:207], v[14:15], v[214:215] op_sel_hi:[1,0]
	v_pk_mul_f32 v[208:209], v[16:17], v[214:215] op_sel_hi:[1,0]
	v_pk_mul_f32 v[210:211], v[6:7], v[214:215] op_sel_hi:[1,0]
	v_pk_mul_f32 v[212:213], v[8:9], v[214:215] op_sel_hi:[1,0]
	v_exp_f32_e32 v206, v206
	v_exp_f32_e32 v207, v207
	v_exp_f32_e32 v208, v208
	v_exp_f32_e32 v209, v209
	v_exp_f32_e32 v210, v210
	v_exp_f32_e32 v211, v211
	v_exp_f32_e32 v212, v212
	v_exp_f32_e32 v213, v213
	v_pk_add_f32 v[206:207], v[206:207], 1.0 op_sel_hi:[1,0]
	v_pk_add_f32 v[208:209], v[208:209], 1.0 op_sel_hi:[1,0]
	v_pk_add_f32 v[210:211], v[210:211], 1.0 op_sel_hi:[1,0]
	v_pk_add_f32 v[212:213], v[212:213], 1.0 op_sel_hi:[1,0]
	v_rcp_f32_e32 v206, v206
	v_rcp_f32_e32 v207, v207
	v_rcp_f32_e32 v208, v208
	v_rcp_f32_e32 v209, v209
	v_rcp_f32_e32 v210, v210
	v_rcp_f32_e32 v211, v211
	v_rcp_f32_e32 v212, v212
	v_rcp_f32_e32 v213, v213
	v_pk_mul_f32 v[206:207], v[14:15], v[206:207]
	v_pk_mul_f32 v[208:209], v[16:17], v[208:209]
	v_pk_mul_f32 v[210:211], v[6:7], v[210:211]
	v_pk_mul_f32 v[212:213], v[8:9], v[212:213]
	v_pk_mul_f32 v[206:207], v[206:207], v[10:11]
	v_pk_mul_f32 v[208:209], v[208:209], v[12:13]
	v_pk_mul_f32 v[210:211], v[210:211], v[2:3]
	v_pk_mul_f32 v[212:213], v[212:213], v[4:5]
	v_cvt_pk_bf16_f32 v10, v206, v207
	v_cvt_pk_bf16_f32 v11, v208, v209
	v_cvt_pk_bf16_f32 v12, v210, v211
	v_cvt_pk_bf16_f32 v13, v212, v213
	v_lshl_add_u64 v[2:3], v[50:51], 0, v[66:67]
	v_lshl_add_u64 v[2:3], v[2:3], 0, v[138:139]
	global_store_dwordx4 v[2:3], v[10:13], off
	s_cbranch_vccnz .LBB0_603
	s_andn2_b64 vcc, exec, s[6:7]
	s_cbranch_vccnz .LBB0_602
	s_barrier
	s_branch .LBB0_602
